# QK-norm epilogue: the two gain loads are issued at the top of the epilogue (before the 16 reduction blocks) instead of after the reduction barrier
# baseline (speedup 1.0000x reference)
.LBB0_137:
	s_andn2_b64 vcc, exec, s[48:49]
	s_cbranch_vccnz .LBB0_171
	s_cmp_lt_i32 s62, 3
	s_cselect_b64 s[48:49], -1, 0
	s_and_b32 s39, s62, -2
	s_cmp_eq_u32 s39, 12
	s_cselect_b64 s[50:51], -1, 0
	s_or_b64 s[50:51], s[48:49], s[50:51]
	v_readlane_b32 s70, v252, 17
	v_readlane_b32 s71, v252, 18
	v_readlane_b32 s72, v252, 19
	v_readlane_b32 s73, v252, 20
	v_readlane_b32 s74, v252, 21
	v_readlane_b32 s75, v252, 22
	v_readlane_b32 s76, v252, 23
	v_readlane_b32 s77, v252, 24
	s_and_b64 s[48:49], s[46:47], exec
	s_cselect_b32 s39, s70, s74
	s_cselect_b32 s41, s71, s75
	s_cselect_b32 s48, s72, s76
	s_cselect_b32 s49, s73, s77
	s_and_b64 s[50:51], s[50:51], exec
	s_cselect_b32 s39, s39, s48
	s_cselect_b32 s41, s41, s49
	s_add_u32 s39, s39, s36
	s_addc_u32 s41, s41, s37
	s_add_u32 s78, s39, s14
	s_addc_u32 s79, s41, 0
	global_load_dwordx4 v[220:223], v206, s[78:79]
	global_load_dwordx4 v[224:227], v206, s[78:79] offset:16
	v_pk_mul_f32 v[178:179], v[128:129], v[166:167] op_sel_hi:[1,0]
	v_pk_mul_f32 v[180:181], v[126:127], v[166:167] op_sel_hi:[1,0]
	v_mul_f32_e32 v149, v179, v179
	v_mul_f32_e32 v147, v181, v181
	v_pk_mul_f32 v[208:209], v[122:123], v[166:167] op_sel_hi:[1,0]
	v_fmac_f32_e32 v147, v180, v180
	v_fmac_f32_e32 v149, v178, v178
	v_and_b32_e32 v145, 64, v198
	v_add_f32_e32 v147, v147, v149
	v_mul_f32_e32 v149, v209, v209
	v_xor_b32_e32 v143, 16, v198
	v_add_u32_e32 v145, 64, v145
	v_pk_mul_f32 v[202:203], v[124:125], v[166:167] op_sel_hi:[1,0]
	v_fmac_f32_e32 v149, v208, v208
	v_cmp_lt_i32_e32 vcc, v143, v145
	v_add_f32_e32 v147, v149, v147
	v_mul_f32_e32 v149, v203, v203
	v_cndmask_b32_e32 v143, v198, v143, vcc
	v_fmac_f32_e32 v149, v202, v202
	v_lshlrev_b32_e32 v143, 2, v143
	v_add_f32_e32 v147, v149, v147
	v_mov_b32_e32 v149, v147
	s_nop 1
	v_permlane16_swap_b32_e32 v147, v149
	v_xor_b32_e32 v151, 32, v198
	v_cmp_lt_i32_e32 vcc, v151, v145
	s_waitcnt lgkmcnt(0)
	v_add_f32_e32 v147, v147, v149
	v_cndmask_b32_e32 v145, v198, v151, vcc
	v_lshlrev_b32_e32 v145, 2, v145
	v_mov_b32_e32 v149, v147
	s_nop 1
	v_permlane32_swap_b32_e32 v147, v149
	s_and_saveexec_b64 s[48:49], s[6:7]
	s_cbranch_execz .LBB0_140
	s_waitcnt lgkmcnt(0)
	v_add_f32_e32 v147, v147, v149
	ds_write_b32 v183, v147

.LBB0_170:
	s_or_b64 exec, exec, s[48:49]
	s_cmp_lt_i32 s62, 3
	s_cselect_b64 s[48:49], -1, 0
	s_and_b32 s39, s62, -2
	s_cmp_eq_u32 s39, 12
	s_cselect_b64 s[50:51], -1, 0
	s_or_b64 vcc, s[48:49], s[50:51]
	v_readlane_b32 s64, v252, 11
	s_and_b64 s[46:47], s[46:47], exec
	v_readlane_b32 s70, v252, 17
	v_readlane_b32 s71, v252, 18
	v_readlane_b32 s72, v252, 19
	v_readlane_b32 s73, v252, 20
	v_readlane_b32 s74, v252, 21
	v_readlane_b32 s75, v252, 22
	v_readlane_b32 s76, v252, 23
	v_readlane_b32 s77, v252, 24
	s_cselect_b32 s39, s70, s74
	s_cselect_b32 s41, s71, s75
	s_cselect_b32 s48, s72, s76
	s_cselect_b32 s49, s73, s77
	s_and_b64 s[46:47], vcc, exec
	s_cselect_b32 s39, s39, s48
	s_cselect_b32 s41, s41, s49
	s_add_u32 s39, s39, s36
	s_addc_u32 s41, s41, s37
	s_add_u32 s46, s39, s14
	s_waitcnt lgkmcnt(0)
	s_barrier
	s_addc_u32 s47, s41, 0
	ds_read_b64 v[202:203], v188
	v_mov_b32_e32 v143, 0x3e38aa3b
	v_cndmask_b32_e32 v196, 1.0, v143, vcc
	v_ashrrev_i32_e32 v175, 31, v174
	v_readlane_b32 s65, v252, 12
	s_waitcnt lgkmcnt(0)
	v_add_f32_e32 v143, v202, v203
	v_fmamk_f32 v143, v143, 0x3c800000, v195
	v_mul_f32_e32 v145, 0x4b800000, v143
	v_cmp_gt_f32_e32 vcc, s2, v143
	v_readlane_b32 s66, v252, 13
	v_readlane_b32 s67, v252, 14
	v_cndmask_b32_e32 v143, v143, v145, vcc
	v_rsq_f32_e32 v143, v143
	v_readlane_b32 s68, v252, 15
	v_readlane_b32 s69, v252, 16
	v_readlane_b32 s78, v252, 25
	v_mul_f32_e32 v145, 0x45800000, v143
	v_cndmask_b32_e32 v143, v143, v145, vcc
	v_mul_f32_e32 v202, v166, v143
	v_pk_mul_f32 v[212:213], v[126:127], v[202:203] op_sel_hi:[1,0]
	v_pk_mul_f32 v[214:215], v[128:129], v[202:203] op_sel_hi:[1,0]
	v_pk_mul_f32 v[216:217], v[122:123], v[202:203] op_sel_hi:[1,0]
	v_pk_mul_f32 v[202:203], v[124:125], v[202:203] op_sel_hi:[1,0]
	v_readlane_b32 s79, v252, 26
	s_waitcnt vmcnt(1)
	v_pk_mul_f32 v[128:129], v[196:197], v[220:221] op_sel_hi:[0,1]
	s_waitcnt vmcnt(0)
	v_pk_mul_f32 v[124:125], v[196:197], v[224:225] op_sel_hi:[0,1]
	v_pk_mul_f32 v[126:127], v[196:197], v[222:223] op_sel_hi:[0,1]
	v_pk_mul_f32 v[122:123], v[196:197], v[226:227] op_sel_hi:[0,1]
	v_pk_mul_f32 v[180:181], v[128:129], v[212:213]
	v_pk_mul_f32 v[210:211], v[124:125], v[216:217]
	v_pk_mul_f32 v[178:179], v[126:127], v[214:215]
	v_pk_mul_f32 v[202:203], v[122:123], v[202:203]
	v_cvt_pk_bf16_f32 v208, v180, v181
	v_cvt_pk_bf16_f32 v209, v178, v179
	v_cvt_pk_bf16_f32 v210, v210, v211
	v_mov_b64_e32 v[178:179], s[0:1]
	v_cvt_pk_bf16_f32 v211, v202, v203
	ds_read_b64 v[180:181], v188 offset:16
	v_mad_i64_i32 v[202:203], s[46:47], v156, s35, v[178:179]
	v_lshlrev_b64 v[156:157], 1, v[174:175]
	v_lshl_add_u64 v[174:175], v[202:203], 0, v[156:157]
	s_waitcnt lgkmcnt(0)
	v_add_f32_e32 v143, v180, v181
	v_fmamk_f32 v143, v143, 0x3c800000, v195
	v_mul_f32_e32 v145, 0x4b800000, v143
	v_cmp_gt_f32_e32 vcc, s2, v143
	global_store_dwordx4 v[174:175], v[208:211], off
	s_nop 0
	v_cndmask_b32_e32 v143, v143, v145, vcc
	v_rsq_f32_e32 v143, v143
	s_nop 0
	v_mul_f32_e32 v145, 0x45800000, v143
	v_cndmask_b32_e32 v143, v143, v145, vcc
	v_mul_f32_e32 v166, v166, v143
	v_pk_mul_f32 v[118:119], v[118:119], v[166:167] op_sel_hi:[1,0]
	v_pk_mul_f32 v[114:115], v[114:115], v[166:167] op_sel_hi:[1,0]
	v_pk_mul_f32 v[116:117], v[116:117], v[166:167] op_sel_hi:[1,0]
	v_pk_mul_f32 v[120:121], v[120:121], v[166:167] op_sel_hi:[1,0]
	v_pk_mul_f32 v[118:119], v[128:129], v[118:119]
	v_pk_mul_f32 v[166:167], v[122:123], v[116:117]
	v_pk_mul_f32 v[116:117], v[124:125], v[114:115]
	v_pk_mul_f32 v[120:121], v[126:127], v[120:121]
	v_cvt_pk_bf16_f32 v114, v118, v119
	s_nop 0
	v_cvt_pk_bf16_f32 v115, v120, v121
	v_cvt_pk_bf16_f32 v116, v116, v117
	v_cvt_pk_bf16_f32 v117, v166, v167
	ds_read_b64 v[118:119], v188 offset:512
	global_store_dwordx4 v[174:175], v[114:117], off offset:256
	s_waitcnt lgkmcnt(0)
	v_add_f32_e32 v118, v118, v119
	v_fmamk_f32 v118, v118, 0x3c800000, v195
	v_mul_f32_e32 v119, 0x4b800000, v118
	v_cmp_gt_f32_e32 vcc, s2, v118
	s_nop 1
	v_cndmask_b32_e32 v118, v118, v119, vcc
	v_rsq_f32_e32 v118, v118
	s_nop 0
	v_mul_f32_e32 v114, 0x45800000, v118
	v_cndmask_b32_e32 v114, v118, v114, vcc
	v_mul_f32_e32 v114, v164, v114
	v_pk_mul_f32 v[110:111], v[110:111], v[114:115] op_sel_hi:[1,0]
	v_pk_mul_f32 v[106:107], v[106:107], v[114:115] op_sel_hi:[1,0]
	v_pk_mul_f32 v[108:109], v[108:109], v[114:115] op_sel_hi:[1,0]
	v_pk_mul_f32 v[112:113], v[112:113], v[114:115] op_sel_hi:[1,0]
	v_pk_mul_f32 v[110:111], v[128:129], v[110:111]
	v_pk_mul_f32 v[114:115], v[122:123], v[108:109]
	v_pk_mul_f32 v[108:109], v[124:125], v[106:107]
	v_pk_mul_f32 v[112:113], v[126:127], v[112:113]
	v_cvt_pk_bf16_f32 v106, v110, v111
	s_nop 0
	v_cvt_pk_bf16_f32 v107, v112, v113
	v_cvt_pk_bf16_f32 v108, v108, v109
	v_cvt_pk_bf16_f32 v109, v114, v115
	ds_read_b64 v[110:111], v188 offset:528
	s_waitcnt lgkmcnt(0)
	v_add_f32_e32 v110, v110, v111
	v_fmamk_f32 v110, v110, 0x3c800000, v195
	v_mul_f32_e32 v111, 0x4b800000, v110
	v_cmp_gt_f32_e32 vcc, s2, v110
	s_nop 1
	v_cndmask_b32_e32 v110, v110, v111, vcc
	v_rsq_f32_e32 v112, v110
	v_mad_i64_i32 v[110:111], s[46:47], v154, s35, v[178:179]
	v_lshl_add_u64 v[110:111], v[110:111], 0, v[156:157]
	global_store_dwordx4 v[110:111], v[106:109], off
	s_nop 1
	v_mul_f32_e32 v106, 0x45800000, v112
	v_cndmask_b32_e32 v106, v112, v106, vcc
	v_mul_f32_e32 v106, v164, v106
	v_pk_mul_f32 v[102:103], v[102:103], v[106:107] op_sel_hi:[1,0]
	v_pk_mul_f32 v[98:99], v[98:99], v[106:107] op_sel_hi:[1,0]
	v_pk_mul_f32 v[100:101], v[100:101], v[106:107] op_sel_hi:[1,0]
	v_pk_mul_f32 v[104:105], v[104:105], v[106:107] op_sel_hi:[1,0]
	v_pk_mul_f32 v[102:103], v[128:129], v[102:103]
	v_pk_mul_f32 v[106:107], v[122:123], v[100:101]
	v_pk_mul_f32 v[100:101], v[124:125], v[98:99]
	v_pk_mul_f32 v[104:105], v[126:127], v[104:105]
	v_cvt_pk_bf16_f32 v98, v102, v103
	s_nop 0
	v_cvt_pk_bf16_f32 v99, v104, v105
	v_cvt_pk_bf16_f32 v100, v100, v101
	v_cvt_pk_bf16_f32 v101, v106, v107
	ds_read_b64 v[102:103], v188 offset:1024
	global_store_dwordx4 v[110:111], v[98:101], off offset:256
	s_waitcnt lgkmcnt(0)
	v_add_f32_e32 v102, v102, v103
	v_fmamk_f32 v102, v102, 0x3c800000, v195
	v_mul_f32_e32 v103, 0x4b800000, v102
	v_cmp_gt_f32_e32 vcc, s2, v102
	s_nop 1
	v_cndmask_b32_e32 v102, v102, v103, vcc
	v_rsq_f32_e32 v102, v102
	s_nop 0
	v_mul_f32_e32 v98, 0x45800000, v102
	v_cndmask_b32_e32 v98, v102, v98, vcc
	v_mul_f32_e32 v98, v162, v98
	v_pk_mul_f32 v[94:95], v[94:95], v[98:99] op_sel_hi:[1,0]
	v_pk_mul_f32 v[90:91], v[90:91], v[98:99] op_sel_hi:[1,0]
	v_pk_mul_f32 v[92:93], v[92:93], v[98:99] op_sel_hi:[1,0]
	v_pk_mul_f32 v[96:97], v[96:97], v[98:99] op_sel_hi:[1,0]
	v_pk_mul_f32 v[94:95], v[128:129], v[94:95]
	v_pk_mul_f32 v[98:99], v[122:123], v[92:93]
	v_pk_mul_f32 v[92:93], v[124:125], v[90:91]
	v_pk_mul_f32 v[96:97], v[126:127], v[96:97]
	v_cvt_pk_bf16_f32 v90, v94, v95
	s_nop 0
	v_cvt_pk_bf16_f32 v91, v96, v97
	v_cvt_pk_bf16_f32 v92, v92, v93
	v_cvt_pk_bf16_f32 v93, v98, v99
	ds_read_b64 v[94:95], v188 offset:1040
	s_waitcnt lgkmcnt(0)
	v_add_f32_e32 v94, v94, v95
	v_fmamk_f32 v94, v94, 0x3c800000, v195
	v_mul_f32_e32 v95, 0x4b800000, v94
	v_cmp_gt_f32_e32 vcc, s2, v94
	s_nop 1
	v_cndmask_b32_e32 v94, v94, v95, vcc
	v_rsq_f32_e32 v96, v94
	v_mad_i64_i32 v[94:95], s[46:47], v152, s35, v[178:179]
	v_lshl_add_u64 v[94:95], v[94:95], 0, v[156:157]
	global_store_dwordx4 v[94:95], v[90:93], off
	s_nop 1
	v_mul_f32_e32 v90, 0x45800000, v96
	v_cndmask_b32_e32 v90, v96, v90, vcc
	v_mul_f32_e32 v90, v162, v90
	v_pk_mul_f32 v[86:87], v[86:87], v[90:91] op_sel_hi:[1,0]
	v_pk_mul_f32 v[82:83], v[82:83], v[90:91] op_sel_hi:[1,0]
	v_pk_mul_f32 v[84:85], v[84:85], v[90:91] op_sel_hi:[1,0]
	v_pk_mul_f32 v[88:89], v[88:89], v[90:91] op_sel_hi:[1,0]
	v_pk_mul_f32 v[86:87], v[128:129], v[86:87]
	v_pk_mul_f32 v[90:91], v[122:123], v[84:85]
	v_pk_mul_f32 v[84:85], v[124:125], v[82:83]
	v_pk_mul_f32 v[88:89], v[126:127], v[88:89]
	v_cvt_pk_bf16_f32 v82, v86, v87
	s_nop 0
	v_cvt_pk_bf16_f32 v83, v88, v89
	v_cvt_pk_bf16_f32 v84, v84, v85
	v_cvt_pk_bf16_f32 v85, v90, v91
	ds_read_b64 v[86:87], v188 offset:1536
	global_store_dwordx4 v[94:95], v[82:85], off offset:256
	s_waitcnt lgkmcnt(0)
	v_add_f32_e32 v86, v86, v87
	v_fmamk_f32 v86, v86, 0x3c800000, v195
	v_mul_f32_e32 v87, 0x4b800000, v86
	v_cmp_gt_f32_e32 vcc, s2, v86
	s_nop 1
	v_cndmask_b32_e32 v86, v86, v87, vcc
	v_rsq_f32_e32 v86, v86
	s_nop 0
	v_mul_f32_e32 v82, 0x45800000, v86
	v_cndmask_b32_e32 v82, v86, v82, vcc
	v_mul_f32_e32 v82, v160, v82
	v_pk_mul_f32 v[78:79], v[78:79], v[82:83] op_sel_hi:[1,0]
	v_pk_mul_f32 v[74:75], v[74:75], v[82:83] op_sel_hi:[1,0]
	v_pk_mul_f32 v[76:77], v[76:77], v[82:83] op_sel_hi:[1,0]
	v_pk_mul_f32 v[80:81], v[80:81], v[82:83] op_sel_hi:[1,0]
	v_pk_mul_f32 v[78:79], v[128:129], v[78:79]
	v_pk_mul_f32 v[82:83], v[122:123], v[76:77]
	v_pk_mul_f32 v[76:77], v[124:125], v[74:75]
	v_pk_mul_f32 v[80:81], v[126:127], v[80:81]
	v_cvt_pk_bf16_f32 v74, v78, v79
	s_nop 0
	v_cvt_pk_bf16_f32 v75, v80, v81
	v_cvt_pk_bf16_f32 v76, v76, v77
	v_cvt_pk_bf16_f32 v77, v82, v83
	ds_read_b64 v[78:79], v188 offset:1552
	s_waitcnt lgkmcnt(0)
	v_add_f32_e32 v78, v78, v79
	v_fmamk_f32 v78, v78, 0x3c800000, v195
	v_mul_f32_e32 v79, 0x4b800000, v78
	v_cmp_gt_f32_e32 vcc, s2, v78
	s_nop 1
	v_cndmask_b32_e32 v78, v78, v79, vcc
	v_rsq_f32_e32 v80, v78
	v_mad_i64_i32 v[78:79], s[46:47], v150, s35, v[178:179]
	v_lshl_add_u64 v[78:79], v[78:79], 0, v[156:157]
	global_store_dwordx4 v[78:79], v[74:77], off
	s_nop 1
	v_mul_f32_e32 v74, 0x45800000, v80
	v_cndmask_b32_e32 v74, v80, v74, vcc
	v_mul_f32_e32 v74, v160, v74
	v_pk_mul_f32 v[70:71], v[70:71], v[74:75] op_sel_hi:[1,0]
	v_pk_mul_f32 v[66:67], v[66:67], v[74:75] op_sel_hi:[1,0]
	v_pk_mul_f32 v[68:69], v[68:69], v[74:75] op_sel_hi:[1,0]
	v_pk_mul_f32 v[72:73], v[72:73], v[74:75] op_sel_hi:[1,0]
	v_pk_mul_f32 v[70:71], v[128:129], v[70:71]
	v_pk_mul_f32 v[74:75], v[122:123], v[68:69]
	v_pk_mul_f32 v[68:69], v[124:125], v[66:67]
	v_pk_mul_f32 v[72:73], v[126:127], v[72:73]
	v_cvt_pk_bf16_f32 v66, v70, v71
	s_nop 0
	v_cvt_pk_bf16_f32 v67, v72, v73
	v_cvt_pk_bf16_f32 v68, v68, v69
	v_cvt_pk_bf16_f32 v69, v74, v75
	ds_read_b64 v[70:71], v189
	global_store_dwordx4 v[78:79], v[66:69], off offset:256
	s_waitcnt lgkmcnt(0)
	v_add_f32_e32 v70, v70, v71
	v_fmamk_f32 v70, v70, 0x3c800000, v195
	v_mul_f32_e32 v71, 0x4b800000, v70
	v_cmp_gt_f32_e32 vcc, s2, v70
	s_nop 1
	v_cndmask_b32_e32 v70, v70, v71, vcc
	v_rsq_f32_e32 v70, v70
	s_nop 0
	v_mul_f32_e32 v66, 0x45800000, v70
	v_cndmask_b32_e32 v66, v70, v66, vcc
	v_mul_f32_e32 v66, v158, v66
	v_pk_mul_f32 v[62:63], v[62:63], v[66:67] op_sel_hi:[1,0]
	v_pk_mul_f32 v[58:59], v[58:59], v[66:67] op_sel_hi:[1,0]
	v_pk_mul_f32 v[60:61], v[60:61], v[66:67] op_sel_hi:[1,0]
	v_pk_mul_f32 v[64:65], v[64:65], v[66:67] op_sel_hi:[1,0]
	v_pk_mul_f32 v[62:63], v[128:129], v[62:63]
	v_pk_mul_f32 v[66:67], v[122:123], v[60:61]
	v_pk_mul_f32 v[60:61], v[124:125], v[58:59]
	v_pk_mul_f32 v[64:65], v[126:127], v[64:65]
	v_cvt_pk_bf16_f32 v58, v62, v63
	s_nop 0
	v_cvt_pk_bf16_f32 v59, v64, v65
	v_cvt_pk_bf16_f32 v60, v60, v61
	v_cvt_pk_bf16_f32 v61, v66, v67
	ds_read_b64 v[62:63], v189 offset:16
	s_waitcnt lgkmcnt(0)
	v_add_f32_e32 v62, v62, v63
	v_fmamk_f32 v62, v62, 0x3c800000, v195
	v_mul_f32_e32 v63, 0x4b800000, v62
	v_cmp_gt_f32_e32 vcc, s2, v62
	s_nop 1
	v_cndmask_b32_e32 v62, v62, v63, vcc
	v_rsq_f32_e32 v64, v62
	v_mad_i64_i32 v[62:63], s[46:47], v148, s35, v[178:179]
	v_lshl_add_u64 v[62:63], v[62:63], 0, v[156:157]
	global_store_dwordx4 v[62:63], v[58:61], off
	s_nop 1
	v_mul_f32_e32 v58, 0x45800000, v64
	v_cndmask_b32_e32 v58, v64, v58, vcc
	v_mul_f32_e32 v58, v158, v58
	v_pk_mul_f32 v[54:55], v[54:55], v[58:59] op_sel_hi:[1,0]
	v_pk_mul_f32 v[50:51], v[50:51], v[58:59] op_sel_hi:[1,0]
	v_pk_mul_f32 v[52:53], v[52:53], v[58:59] op_sel_hi:[1,0]
	v_pk_mul_f32 v[56:57], v[56:57], v[58:59] op_sel_hi:[1,0]
	v_pk_mul_f32 v[54:55], v[128:129], v[54:55]
	v_pk_mul_f32 v[58:59], v[122:123], v[52:53]
	v_pk_mul_f32 v[52:53], v[124:125], v[50:51]
	v_pk_mul_f32 v[56:57], v[126:127], v[56:57]
	v_cvt_pk_bf16_f32 v50, v54, v55
	s_nop 0
	v_cvt_pk_bf16_f32 v51, v56, v57
	v_cvt_pk_bf16_f32 v52, v52, v53
	v_cvt_pk_bf16_f32 v53, v58, v59
	ds_read_b64 v[54:55], v190
	global_store_dwordx4 v[62:63], v[50:53], off offset:256
	s_waitcnt lgkmcnt(0)
	v_add_f32_e32 v54, v54, v55
	v_fmamk_f32 v54, v54, 0x3c800000, v195
	v_mul_f32_e32 v55, 0x4b800000, v54
	v_cmp_gt_f32_e32 vcc, s2, v54
	s_nop 1
	v_cndmask_b32_e32 v54, v54, v55, vcc
	v_rsq_f32_e32 v54, v54
	s_nop 0
	v_mul_f32_e32 v50, 0x45800000, v54
	v_cndmask_b32_e32 v50, v54, v50, vcc
	v_mul_f32_e32 v50, v172, v50
	v_pk_mul_f32 v[46:47], v[46:47], v[50:51] op_sel_hi:[1,0]
	v_pk_mul_f32 v[42:43], v[42:43], v[50:51] op_sel_hi:[1,0]
	v_pk_mul_f32 v[44:45], v[44:45], v[50:51] op_sel_hi:[1,0]
	v_pk_mul_f32 v[48:49], v[48:49], v[50:51] op_sel_hi:[1,0]
	v_pk_mul_f32 v[46:47], v[128:129], v[46:47]
	v_pk_mul_f32 v[50:51], v[122:123], v[44:45]
	v_pk_mul_f32 v[44:45], v[124:125], v[42:43]
	v_pk_mul_f32 v[48:49], v[126:127], v[48:49]
	v_cvt_pk_bf16_f32 v42, v46, v47
	s_nop 0
	v_cvt_pk_bf16_f32 v43, v48, v49
	v_cvt_pk_bf16_f32 v44, v44, v45
	v_cvt_pk_bf16_f32 v45, v50, v51
	ds_read_b64 v[46:47], v188 offset:4624
	s_waitcnt lgkmcnt(0)
	v_add_f32_e32 v46, v46, v47
	v_fmamk_f32 v46, v46, 0x3c800000, v195
	v_mul_f32_e32 v47, 0x4b800000, v46
	v_cmp_gt_f32_e32 vcc, s2, v46
	s_nop 1
	v_cndmask_b32_e32 v46, v46, v47, vcc
	v_rsq_f32_e32 v48, v46
	v_mad_i64_i32 v[46:47], s[46:47], v146, s35, v[178:179]
	v_lshl_add_u64 v[46:47], v[46:47], 0, v[156:157]
	global_store_dwordx4 v[46:47], v[42:45], off
	s_nop 1
	v_mul_f32_e32 v42, 0x45800000, v48
	v_cndmask_b32_e32 v42, v48, v42, vcc
	v_mul_f32_e32 v42, v172, v42
	v_pk_mul_f32 v[38:39], v[38:39], v[42:43] op_sel_hi:[1,0]
	v_pk_mul_f32 v[34:35], v[34:35], v[42:43] op_sel_hi:[1,0]
	v_pk_mul_f32 v[36:37], v[36:37], v[42:43] op_sel_hi:[1,0]
	v_pk_mul_f32 v[40:41], v[40:41], v[42:43] op_sel_hi:[1,0]
	v_pk_mul_f32 v[38:39], v[128:129], v[38:39]
	v_pk_mul_f32 v[42:43], v[122:123], v[36:37]
	v_pk_mul_f32 v[36:37], v[124:125], v[34:35]
	v_pk_mul_f32 v[40:41], v[126:127], v[40:41]
	v_cvt_pk_bf16_f32 v34, v38, v39
	s_nop 0
	v_cvt_pk_bf16_f32 v35, v40, v41
	v_cvt_pk_bf16_f32 v36, v36, v37
	v_cvt_pk_bf16_f32 v37, v42, v43
	ds_read_b64 v[38:39], v191
	global_store_dwordx4 v[46:47], v[34:37], off offset:256
	s_waitcnt lgkmcnt(0)
	v_add_f32_e32 v38, v38, v39
	v_fmamk_f32 v38, v38, 0x3c800000, v195
	v_mul_f32_e32 v39, 0x4b800000, v38
	v_cmp_gt_f32_e32 vcc, s2, v38
	s_nop 1
	v_cndmask_b32_e32 v38, v38, v39, vcc
	v_rsq_f32_e32 v38, v38
	s_nop 0
	v_mul_f32_e32 v34, 0x45800000, v38
	v_cndmask_b32_e32 v34, v38, v34, vcc
	v_mul_f32_e32 v34, v170, v34
	v_pk_mul_f32 v[30:31], v[30:31], v[34:35] op_sel_hi:[1,0]
	v_pk_mul_f32 v[26:27], v[26:27], v[34:35] op_sel_hi:[1,0]
	v_pk_mul_f32 v[28:29], v[28:29], v[34:35] op_sel_hi:[1,0]
	v_pk_mul_f32 v[32:33], v[32:33], v[34:35] op_sel_hi:[1,0]
	v_pk_mul_f32 v[30:31], v[128:129], v[30:31]
	v_pk_mul_f32 v[34:35], v[122:123], v[28:29]
	v_pk_mul_f32 v[28:29], v[124:125], v[26:27]
	v_pk_mul_f32 v[32:33], v[126:127], v[32:33]
	v_cvt_pk_bf16_f32 v26, v30, v31
	s_nop 0
	v_cvt_pk_bf16_f32 v27, v32, v33
	v_cvt_pk_bf16_f32 v28, v28, v29
	v_cvt_pk_bf16_f32 v29, v34, v35
	ds_read_b64 v[30:31], v188 offset:5136
	s_waitcnt lgkmcnt(0)
	v_add_f32_e32 v30, v30, v31
	v_fmamk_f32 v30, v30, 0x3c800000, v195
	v_mul_f32_e32 v31, 0x4b800000, v30
	v_cmp_gt_f32_e32 vcc, s2, v30
	s_nop 1
	v_cndmask_b32_e32 v30, v30, v31, vcc
	v_rsq_f32_e32 v32, v30
	v_mad_i64_i32 v[30:31], s[46:47], v144, s35, v[178:179]
	v_lshl_add_u64 v[30:31], v[30:31], 0, v[156:157]
	global_store_dwordx4 v[30:31], v[26:29], off
	s_nop 1
	v_mul_f32_e32 v26, 0x45800000, v32
	v_cndmask_b32_e32 v26, v32, v26, vcc
	v_mul_f32_e32 v26, v170, v26
	v_pk_mul_f32 v[22:23], v[22:23], v[26:27] op_sel_hi:[1,0]
	v_pk_mul_f32 v[18:19], v[18:19], v[26:27] op_sel_hi:[1,0]
	v_pk_mul_f32 v[20:21], v[20:21], v[26:27] op_sel_hi:[1,0]
	v_pk_mul_f32 v[24:25], v[24:25], v[26:27] op_sel_hi:[1,0]
	v_pk_mul_f32 v[22:23], v[128:129], v[22:23]
	v_pk_mul_f32 v[26:27], v[122:123], v[20:21]
	v_pk_mul_f32 v[20:21], v[124:125], v[18:19]
	v_pk_mul_f32 v[24:25], v[126:127], v[24:25]
	v_cvt_pk_bf16_f32 v18, v22, v23
	s_nop 0
	v_cvt_pk_bf16_f32 v19, v24, v25
	v_cvt_pk_bf16_f32 v20, v20, v21
	v_cvt_pk_bf16_f32 v21, v26, v27
	ds_read_b64 v[22:23], v192
	global_store_dwordx4 v[30:31], v[18:21], off offset:256
	s_waitcnt lgkmcnt(0)
	v_add_f32_e32 v22, v22, v23
	v_fmamk_f32 v22, v22, 0x3c800000, v195
	v_mul_f32_e32 v23, 0x4b800000, v22
	v_cmp_gt_f32_e32 vcc, s2, v22
	s_nop 1
	v_cndmask_b32_e32 v22, v22, v23, vcc
	v_rsq_f32_e32 v22, v22
	s_nop 0
	v_mul_f32_e32 v18, 0x45800000, v22
	v_cndmask_b32_e32 v18, v22, v18, vcc
	v_mul_f32_e32 v18, v168, v18
	v_pk_mul_f32 v[14:15], v[14:15], v[18:19] op_sel_hi:[1,0]
	v_pk_mul_f32 v[10:11], v[10:11], v[18:19] op_sel_hi:[1,0]
	v_pk_mul_f32 v[12:13], v[12:13], v[18:19] op_sel_hi:[1,0]
	v_pk_mul_f32 v[16:17], v[16:17], v[18:19] op_sel_hi:[1,0]
	v_pk_mul_f32 v[14:15], v[128:129], v[14:15]
	v_pk_mul_f32 v[18:19], v[122:123], v[12:13]
	v_pk_mul_f32 v[12:13], v[124:125], v[10:11]
	v_pk_mul_f32 v[16:17], v[126:127], v[16:17]
	v_cvt_pk_bf16_f32 v10, v14, v15
	s_nop 0
	v_cvt_pk_bf16_f32 v11, v16, v17
	v_cvt_pk_bf16_f32 v12, v12, v13
	v_cvt_pk_bf16_f32 v13, v18, v19
	ds_read_b64 v[14:15], v188 offset:5648
	s_waitcnt lgkmcnt(0)
	v_add_f32_e32 v14, v14, v15
	v_fmamk_f32 v14, v14, 0x3c800000, v195
	v_mul_f32_e32 v15, 0x4b800000, v14
	v_cmp_gt_f32_e32 vcc, s2, v14
	s_nop 1
	v_cndmask_b32_e32 v14, v14, v15, vcc
	v_rsq_f32_e32 v16, v14
	v_mad_i64_i32 v[14:15], s[46:47], v142, s35, v[178:179]
	v_lshl_add_u64 v[14:15], v[14:15], 0, v[156:157]
	global_store_dwordx4 v[14:15], v[10:13], off
	s_nop 1
	v_mul_f32_e32 v10, 0x45800000, v16
	v_cndmask_b32_e32 v10, v16, v10, vcc
	v_mul_f32_e32 v10, v168, v10
	v_pk_mul_f32 v[2:3], v[2:3], v[10:11] op_sel_hi:[1,0]
	v_pk_mul_f32 v[4:5], v[4:5], v[10:11] op_sel_hi:[1,0]
	v_pk_mul_f32 v[6:7], v[6:7], v[10:11] op_sel_hi:[1,0]
	v_pk_mul_f32 v[8:9], v[8:9], v[10:11] op_sel_hi:[1,0]
	v_pk_mul_f32 v[10:11], v[122:123], v[4:5]
	v_pk_mul_f32 v[4:5], v[124:125], v[2:3]
	v_pk_mul_f32 v[8:9], v[126:127], v[8:9]
	v_pk_mul_f32 v[6:7], v[128:129], v[6:7]
	s_nop 0
	v_cvt_pk_bf16_f32 v2, v6, v7
	v_cvt_pk_bf16_f32 v3, v8, v9
	v_cvt_pk_bf16_f32 v4, v4, v5
	v_cvt_pk_bf16_f32 v5, v10, v11
	global_store_dwordx4 v[14:15], v[2:5], off offset:256
